# kind-0 epilogue: zero-fill of the first row group's shifted products via DPP bound_ctrl instead of 16 explicit zero moves
# baseline (speedup 1.0000x reference)
; __device__ __forceinline__ float siluf_(float x) { return x * sigmoidf_(x); }
; __device__ __forceinline__ u32x2 pk4(f32x4 v) { u32x2 r; r.x = pk_bf16(v[0], v[1]); r.y = pk_bf16(v[2], v[3]); return r; }
; template <int CTRL> __device__ __forceinline__ float dppf(float old, float v) { return __int_as_float(__builtin_amdgcn_update_dpp(__float_as_int(old), __float_as_int(v), CTRL, 0xf, 0xf, false)); }
; __device__ __forceinline__ int pf(int fq) { return (fq >> 1) | ((fq & 1) << 1); }
;     __device__ __forceinline__ void operator()(const f32x4 (&acc)[2][2][4][2], const Unit& u, int wr, int wc, int fr, int fq) const {
;         if (u.kind <= 2) {
;             const int chw = (u.pn & 15) * 64 + wc * 16, ch = chw + pf(fq) * 4;
;             const int rowb = u.pm * 256 + wr * 64 + fr;
;             if (u.kind == 0) {
;                 const f32x4 w0 = *(const f32x4*)(convw + ch), w1 = *(const f32x4*)(convw + 1024 + ch), w2 = *(const f32x4*)(convw + 2048 + ch);
; #pragma unroll
;                 for (int ai = 0; ai < 2; ++ai) {
;                     const int blk = u.pm * 4 + ai * 2 + wr;
;                     f32x4 pprev = (f32x4){0.f, 0.f, 0.f, 0.f}; u32x2 hv[4];
; #pragma unroll
;                     for (int m = 0; m < 4; ++m) {
;                         const f32x4 Bv = acc[ai][0][m][0], Cv = acc[ai][0][m][1], Xv = acc[ai][1][m][0], Zv = acc[ai][1][m][1];
;                         const f32x4 p = Cv * Xv; f32x4 ga, p1, p2;
; #pragma unroll
;                         for (int j = 0; j < 4; ++j) {
;                             ga[j] = siluf_(Zv[j]) * Bv[j];
;                             const float r1 = (m > 0) ? dppf<0x121>(0.f, pprev[j]) : 0.f, r2 = (m > 0) ? dppf<0x122>(0.f, pprev[j]) : 0.f;
;                             p1[j] = dppf<0x111>(r1, p[j]); p2[j] = dppf<0x112>(r2, p[j]);
;                         }
;                         const f32x4 cv = w2 * p + w1 * p1 + w0 * p2;
;                         hv[m] = pk4(ga * cv);
;                         if (m == 3 && fr >= 14) *(u32x2*)(PAT + (size_t)(blk * 2 + (fr - 14)) * 1024 + ch) = pk4(p);
;                         if (m == 0 && fr < 2) *(u32x2*)(GAH + (size_t)(blk * 2 + fr) * 1024 + ch) = pk4(ga);
;                         pprev = p;
;                     }
.Lp1e_k0h:
	v_mbcnt_lo_u32_b32 v240, -1, 0
	v_mbcnt_hi_u32_b32 v240, -1, v240
	v_readlane_b32 s4, v255, 19
	v_readlane_b32 s98, v255, 27
	v_readlane_b32 s99, v255, 28
	v_readlane_b32 s100, v255, 29
	v_readlane_b32 s101, v255, 30
	v_and_b32_e32 v241, 15, v240
	v_lshrrev_b32_e32 v242, 4, v240
	s_lshr_b32 s4, s4, 6
	s_lshr_b32 s5, s4, 2
	s_and_b32 s30, s4, 3
	s_and_b32 s64, s90, 15
	s_lshl_b32 s64, s64, 6
	s_lshl_b32 vcc_lo, s30, 4
	s_add_i32 s64, s64, vcc_lo
	v_lshrrev_b32_e32 v213, 1, v242
	v_and_b32_e32 v214, 1, v242
	v_lshl_or_b32 v210, v214, 1, v213
	v_lshl_add_u32 v210, v210, 2, s64
	v_lshlrev_b32_e32 v211, 1, v210
	v_lshlrev_b32_e32 v210, 2, v210
	global_load_dwordx4 v[176:179], v210, s[44:45]
	global_load_dwordx4 v[180:183], v210, s[98:99]
	global_load_dwordx4 v[184:187], v210, s[100:101]
	s_lshl_b32 s31, s96, 8
	s_lshl_b32 vcc_lo, s5, 6
	s_add_i32 s31, s31, vcc_lo
	v_lshl_add_u32 v212, v213, 4, v241
	v_add_u32_e32 v212, s31, v212
	v_lshlrev_b32_e32 v212, 11, v212
	v_lshl_add_u32 v214, v214, 3, s64
	v_lshl_add_u32 v212, v214, 1, v212
	s_lshl_b32 s31, s96, 3
	s_lshl_b32 vcc_lo, s5, 1
	s_add_i32 s31, s31, vcc_lo
	v_add_u32_e32 v213, s31, v241
	v_lshl_add_u32 v211, v213, 11, v211
	v_readlane_b32 s98, v255, 11
	v_readlane_b32 s99, v255, 12
	s_mov_b32 s42, 0xbfb8aa3b
	s_mov_b32 s43, 1.0
	v_pk_mul_f32 v[128:129], v[112:113], s[42:43] op_sel_hi:[1,0]
	v_pk_mul_f32 v[130:131], v[114:115], s[42:43] op_sel_hi:[1,0]
	v_pk_mul_f32 v[120:121], v[124:125], v[120:121]
	v_pk_mul_f32 v[122:123], v[126:127], v[122:123]
	v_exp_f32_e32 v128, v128
	v_exp_f32_e32 v129, v129
	v_exp_f32_e32 v130, v130
	v_exp_f32_e32 v131, v131
	v_pk_add_f32 v[128:129], v[128:129], s[42:43] op_sel:[0,1] op_sel_hi:[1,1]
	v_pk_add_f32 v[130:131], v[130:131], s[42:43] op_sel:[0,1] op_sel_hi:[1,1]
	v_mov_b32_dpp v132, v120 row_shr:1 row_mask:0xf bank_mask:0xf bound_ctrl:1
	v_mov_b32_dpp v136, v120 row_shr:2 row_mask:0xf bank_mask:0xf bound_ctrl:1
	v_mov_b32_dpp v133, v121 row_shr:1 row_mask:0xf bank_mask:0xf bound_ctrl:1
	v_mov_b32_dpp v137, v121 row_shr:2 row_mask:0xf bank_mask:0xf bound_ctrl:1
	v_mov_b32_dpp v134, v122 row_shr:1 row_mask:0xf bank_mask:0xf bound_ctrl:1
	v_mov_b32_dpp v138, v122 row_shr:2 row_mask:0xf bank_mask:0xf bound_ctrl:1
	v_mov_b32_dpp v135, v123 row_shr:1 row_mask:0xf bank_mask:0xf bound_ctrl:1
	v_mov_b32_dpp v139, v123 row_shr:2 row_mask:0xf bank_mask:0xf bound_ctrl:1
	v_rcp_f32_e32 v128, v128
	v_rcp_f32_e32 v129, v129
	v_rcp_f32_e32 v130, v130
	v_rcp_f32_e32 v131, v131
	s_waitcnt vmcnt(0)
	v_pk_mul_f32 v[132:133], v[180:181], v[132:133]
	v_pk_mul_f32 v[134:135], v[182:183], v[134:135]
	v_pk_mul_f32 v[128:129], v[112:113], v[128:129]
	v_pk_mul_f32 v[130:131], v[114:115], v[130:131]
	v_pk_fma_f32 v[132:133], v[184:185], v[120:121], v[132:133]
	v_pk_fma_f32 v[134:135], v[186:187], v[122:123], v[134:135]
	v_pk_mul_f32 v[116:117], v[116:117], v[128:129]
	v_pk_mul_f32 v[118:119], v[118:119], v[130:131]
	v_pk_fma_f32 v[132:133], v[176:177], v[136:137], v[132:133]
	v_pk_fma_f32 v[134:135], v[178:179], v[138:139], v[134:135]
	v_cvt_pk_bf16_f32 v208, v116, v117
	v_cvt_pk_bf16_f32 v209, v118, v119
	v_pk_mul_f32 v[132:133], v[116:117], v[132:133]
	v_pk_mul_f32 v[134:135], v[118:119], v[134:135]
	v_cmp_gt_u32_e32 vcc, 2, v241
	s_add_u32 s100, s60, 0x0
	s_addc_u32 s101, s61, 0
	s_nop 2
	s_and_saveexec_b64 s[4:5], vcc
	global_store_dwordx2 v211, v[208:209], s[100:101]
	s_mov_b64 exec, s[4:5]
	v_cvt_pk_bf16_f32 v198, v132, v133
	v_cvt_pk_bf16_f32 v199, v134, v135
	v_pk_mul_f32 v[128:129], v[80:81], s[42:43] op_sel_hi:[1,0]
	v_pk_mul_f32 v[130:131], v[82:83], s[42:43] op_sel_hi:[1,0]
	v_pk_mul_f32 v[104:105], v[108:109], v[104:105]
	v_pk_mul_f32 v[106:107], v[110:111], v[106:107]
	v_exp_f32_e32 v128, v128
	v_exp_f32_e32 v129, v129
	v_exp_f32_e32 v130, v130
	v_exp_f32_e32 v131, v131
	v_mov_b32_dpp v132, v120 row_ror:1 row_mask:0xf bank_mask:0xf
	v_mov_b32_dpp v136, v120 row_ror:2 row_mask:0xf bank_mask:0xf
	v_mov_b32_dpp v133, v121 row_ror:1 row_mask:0xf bank_mask:0xf
	v_mov_b32_dpp v137, v121 row_ror:2 row_mask:0xf bank_mask:0xf
	v_mov_b32_dpp v134, v122 row_ror:1 row_mask:0xf bank_mask:0xf
	v_mov_b32_dpp v138, v122 row_ror:2 row_mask:0xf bank_mask:0xf
	v_mov_b32_dpp v135, v123 row_ror:1 row_mask:0xf bank_mask:0xf
	v_mov_b32_dpp v139, v123 row_ror:2 row_mask:0xf bank_mask:0xf
	v_pk_add_f32 v[128:129], v[128:129], s[42:43] op_sel:[0,1] op_sel_hi:[1,1]
	v_pk_add_f32 v[130:131], v[130:131], s[42:43] op_sel:[0,1] op_sel_hi:[1,1]
	v_mov_b32_dpp v132, v104 row_shr:1 row_mask:0xf bank_mask:0xf
	v_mov_b32_dpp v136, v104 row_shr:2 row_mask:0xf bank_mask:0xf
	v_mov_b32_dpp v133, v105 row_shr:1 row_mask:0xf bank_mask:0xf
	v_mov_b32_dpp v137, v105 row_shr:2 row_mask:0xf bank_mask:0xf
	v_mov_b32_dpp v134, v106 row_shr:1 row_mask:0xf bank_mask:0xf
	v_mov_b32_dpp v138, v106 row_shr:2 row_mask:0xf bank_mask:0xf
	v_mov_b32_dpp v135, v107 row_shr:1 row_mask:0xf bank_mask:0xf
	v_mov_b32_dpp v139, v107 row_shr:2 row_mask:0xf bank_mask:0xf
	v_rcp_f32_e32 v128, v128
	v_rcp_f32_e32 v129, v129
	v_rcp_f32_e32 v130, v130
	v_rcp_f32_e32 v131, v131
	v_pk_mul_f32 v[132:133], v[180:181], v[132:133]
	v_pk_mul_f32 v[134:135], v[182:183], v[134:135]
	v_pk_mul_f32 v[128:129], v[80:81], v[128:129]
	v_pk_mul_f32 v[130:131], v[82:83], v[130:131]
	v_pk_fma_f32 v[132:133], v[184:185], v[104:105], v[132:133]
	v_pk_fma_f32 v[134:135], v[186:187], v[106:107], v[134:135]
	v_pk_mul_f32 v[84:85], v[84:85], v[128:129]
	v_pk_mul_f32 v[86:87], v[86:87], v[130:131]
	v_pk_fma_f32 v[132:133], v[176:177], v[136:137], v[132:133]
	v_pk_fma_f32 v[134:135], v[178:179], v[138:139], v[134:135]
	v_pk_mul_f32 v[132:133], v[84:85], v[132:133]
; __device__ __forceinline__ float siluf_(float x) { return x * sigmoidf_(x); }
; __device__ __forceinline__ u32x2 pk4(f32x4 v) { u32x2 r; r.x = pk_bf16(v[0], v[1]); r.y = pk_bf16(v[2], v[3]); return r; }
; template <int CTRL> __device__ __forceinline__ float dppf(float old, float v) { return __int_as_float(__builtin_amdgcn_update_dpp(__float_as_int(old), __float_as_int(v), CTRL, 0xf, 0xf, false)); }
;     __device__ __forceinline__ void operator()(const f32x4 (&acc)[2][2][4][2], const Unit& u, int wr, int wc, int fr, int fq) const {
;     ...
;                 const f32x4 w0 = *(const f32x4*)(convw + ch), w1 = *(const f32x4*)(convw + 1024 + ch), w2 = *(const f32x4*)(convw + 2048 + ch);
; #pragma unroll
;                 for (int ai = 0; ai < 2; ++ai) {
;                     const int blk = u.pm * 4 + ai * 2 + wr;
;                     f32x4 pprev = (f32x4){0.f, 0.f, 0.f, 0.f}; u32x2 hv[4];
; #pragma unroll
;                     for (int m = 0; m < 4; ++m) {
;                         const f32x4 Bv = acc[ai][0][m][0], Cv = acc[ai][0][m][1], Xv = acc[ai][1][m][0], Zv = acc[ai][1][m][1];
;                         const f32x4 p = Cv * Xv; f32x4 ga, p1, p2;
; #pragma unroll
;                         for (int j = 0; j < 4; ++j) {
;                             ga[j] = siluf_(Zv[j]) * Bv[j];
;                             const float r1 = (m > 0) ? dppf<0x121>(0.f, pprev[j]) : 0.f, r2 = (m > 0) ? dppf<0x122>(0.f, pprev[j]) : 0.f;
;                             p1[j] = dppf<0x111>(r1, p[j]); p2[j] = dppf<0x112>(r2, p[j]);
;                         }
;                         const f32x4 cv = w2 * p + w1 * p1 + w0 * p2;
;                         hv[m] = pk4(ga * cv);
;                         if (m == 3 && fr >= 14) *(u32x2*)(PAT + (size_t)(blk * 2 + (fr - 14)) * 1024 + ch) = pk4(p);
;                         if (m == 0 && fr < 2) *(u32x2*)(GAH + (size_t)(blk * 2 + fr) * 1024 + ch) = pk4(ga);
;                         pprev = p;
;                     }
; #pragma unroll
;                     for (int pr = 0; pr < 2; ++pr) store_pair16(HA + (size_t)(rowb + ai * 128 + pr * 32) * 1024 + chw, hv[2 * pr], hv[2 * pr + 1], fq);
	v_pk_mul_f32 v[134:135], v[86:87], v[134:135]
	v_cvt_pk_bf16_f32 v200, v132, v133
	v_cvt_pk_bf16_f32 v201, v134, v135
	v_pk_mul_f32 v[128:129], v[72:73], s[42:43] op_sel_hi:[1,0]
	v_pk_mul_f32 v[130:131], v[74:75], s[42:43] op_sel_hi:[1,0]
	v_pk_mul_f32 v[96:97], v[100:101], v[96:97]
	v_pk_mul_f32 v[98:99], v[102:103], v[98:99]
	v_exp_f32_e32 v128, v128
	v_exp_f32_e32 v129, v129
	v_exp_f32_e32 v130, v130
	v_exp_f32_e32 v131, v131
	v_mov_b32_dpp v132, v104 row_ror:1 row_mask:0xf bank_mask:0xf
	v_mov_b32_dpp v136, v104 row_ror:2 row_mask:0xf bank_mask:0xf
	v_mov_b32_dpp v133, v105 row_ror:1 row_mask:0xf bank_mask:0xf
	v_mov_b32_dpp v137, v105 row_ror:2 row_mask:0xf bank_mask:0xf
	v_mov_b32_dpp v134, v106 row_ror:1 row_mask:0xf bank_mask:0xf
	v_mov_b32_dpp v138, v106 row_ror:2 row_mask:0xf bank_mask:0xf
	v_mov_b32_dpp v135, v107 row_ror:1 row_mask:0xf bank_mask:0xf
	v_mov_b32_dpp v139, v107 row_ror:2 row_mask:0xf bank_mask:0xf
	v_pk_add_f32 v[128:129], v[128:129], s[42:43] op_sel:[0,1] op_sel_hi:[1,1]
	v_pk_add_f32 v[130:131], v[130:131], s[42:43] op_sel:[0,1] op_sel_hi:[1,1]
	v_mov_b32_dpp v132, v96 row_shr:1 row_mask:0xf bank_mask:0xf
	v_mov_b32_dpp v136, v96 row_shr:2 row_mask:0xf bank_mask:0xf
	v_mov_b32_dpp v133, v97 row_shr:1 row_mask:0xf bank_mask:0xf
	v_mov_b32_dpp v137, v97 row_shr:2 row_mask:0xf bank_mask:0xf
	v_mov_b32_dpp v134, v98 row_shr:1 row_mask:0xf bank_mask:0xf
	v_mov_b32_dpp v138, v98 row_shr:2 row_mask:0xf bank_mask:0xf
	v_mov_b32_dpp v135, v99 row_shr:1 row_mask:0xf bank_mask:0xf
	v_mov_b32_dpp v139, v99 row_shr:2 row_mask:0xf bank_mask:0xf
	v_rcp_f32_e32 v128, v128
	v_rcp_f32_e32 v129, v129
	v_rcp_f32_e32 v130, v130
	v_rcp_f32_e32 v131, v131
	v_pk_mul_f32 v[132:133], v[180:181], v[132:133]
	v_pk_mul_f32 v[134:135], v[182:183], v[134:135]
	v_pk_mul_f32 v[128:129], v[72:73], v[128:129]
	v_pk_mul_f32 v[130:131], v[74:75], v[130:131]
	v_pk_fma_f32 v[132:133], v[184:185], v[96:97], v[132:133]
	v_pk_fma_f32 v[134:135], v[186:187], v[98:99], v[134:135]
	v_pk_mul_f32 v[76:77], v[76:77], v[128:129]
	v_pk_mul_f32 v[78:79], v[78:79], v[130:131]
	v_pk_fma_f32 v[132:133], v[176:177], v[136:137], v[132:133]
	v_pk_fma_f32 v[134:135], v[178:179], v[138:139], v[134:135]
	v_pk_mul_f32 v[132:133], v[76:77], v[132:133]
	v_pk_mul_f32 v[134:135], v[78:79], v[134:135]
	v_cvt_pk_bf16_f32 v202, v132, v133
	v_cvt_pk_bf16_f32 v203, v134, v135
	v_pk_mul_f32 v[128:129], v[64:65], s[42:43] op_sel_hi:[1,0]
	v_pk_mul_f32 v[130:131], v[66:67], s[42:43] op_sel_hi:[1,0]
	v_pk_mul_f32 v[88:89], v[92:93], v[88:89]
	v_pk_mul_f32 v[90:91], v[94:95], v[90:91]
	v_exp_f32_e32 v128, v128
	v_exp_f32_e32 v129, v129
	v_exp_f32_e32 v130, v130
	v_exp_f32_e32 v131, v131
	v_mov_b32_dpp v132, v96 row_ror:1 row_mask:0xf bank_mask:0xf
	v_mov_b32_dpp v136, v96 row_ror:2 row_mask:0xf bank_mask:0xf
	v_mov_b32_dpp v133, v97 row_ror:1 row_mask:0xf bank_mask:0xf
	v_mov_b32_dpp v137, v97 row_ror:2 row_mask:0xf bank_mask:0xf
	v_mov_b32_dpp v134, v98 row_ror:1 row_mask:0xf bank_mask:0xf
	v_mov_b32_dpp v138, v98 row_ror:2 row_mask:0xf bank_mask:0xf
	v_mov_b32_dpp v135, v99 row_ror:1 row_mask:0xf bank_mask:0xf
	v_mov_b32_dpp v139, v99 row_ror:2 row_mask:0xf bank_mask:0xf
	v_pk_add_f32 v[128:129], v[128:129], s[42:43] op_sel:[0,1] op_sel_hi:[1,1]
	v_pk_add_f32 v[130:131], v[130:131], s[42:43] op_sel:[0,1] op_sel_hi:[1,1]
	v_mov_b32_dpp v132, v88 row_shr:1 row_mask:0xf bank_mask:0xf
	v_mov_b32_dpp v136, v88 row_shr:2 row_mask:0xf bank_mask:0xf
	v_mov_b32_dpp v133, v89 row_shr:1 row_mask:0xf bank_mask:0xf
	v_mov_b32_dpp v137, v89 row_shr:2 row_mask:0xf bank_mask:0xf
	v_mov_b32_dpp v134, v90 row_shr:1 row_mask:0xf bank_mask:0xf
	v_mov_b32_dpp v138, v90 row_shr:2 row_mask:0xf bank_mask:0xf
	v_mov_b32_dpp v135, v91 row_shr:1 row_mask:0xf bank_mask:0xf
	v_mov_b32_dpp v139, v91 row_shr:2 row_mask:0xf bank_mask:0xf
	v_rcp_f32_e32 v128, v128
	v_rcp_f32_e32 v129, v129
	v_rcp_f32_e32 v130, v130
	v_rcp_f32_e32 v131, v131
	v_pk_mul_f32 v[132:133], v[180:181], v[132:133]
	v_pk_mul_f32 v[134:135], v[182:183], v[134:135]
	v_pk_mul_f32 v[128:129], v[64:65], v[128:129]
	v_pk_mul_f32 v[130:131], v[66:67], v[130:131]
	v_pk_fma_f32 v[132:133], v[184:185], v[88:89], v[132:133]
	v_pk_fma_f32 v[134:135], v[186:187], v[90:91], v[134:135]
	v_pk_mul_f32 v[68:69], v[68:69], v[128:129]
	v_pk_mul_f32 v[70:71], v[70:71], v[130:131]
	v_pk_fma_f32 v[132:133], v[176:177], v[136:137], v[132:133]
	v_pk_fma_f32 v[134:135], v[178:179], v[138:139], v[134:135]
	v_cvt_pk_bf16_f32 v206, v88, v89
	v_cvt_pk_bf16_f32 v207, v90, v91
	v_pk_mul_f32 v[132:133], v[68:69], v[132:133]
	v_pk_mul_f32 v[134:135], v[70:71], v[134:135]
	v_cmp_lt_u32_e32 vcc, 13, v241
	s_sub_u32 s100, s58, 0x7000
	s_subb_u32 s101, s59, 0
	s_nop 2
	s_and_saveexec_b64 s[4:5], vcc
	global_store_dwordx2 v211, v[206:207], s[100:101]
	s_mov_b64 exec, s[4:5]
	v_cvt_pk_bf16_f32 v204, v132, v133
	v_cvt_pk_bf16_f32 v205, v134, v135
	s_add_u32 s100, s98, 0x0
	s_addc_u32 s101, s99, 0
	v_permlane32_swap_b32_e32 v198, v200
	v_permlane32_swap_b32_e32 v199, v201
	global_store_dwordx4 v212, v[198:201], s[100:101]
	s_add_u32 s100, s98, 0x10000
	s_addc_u32 s101, s99, 0
	v_permlane32_swap_b32_e32 v202, v204
	v_permlane32_swap_b32_e32 v203, v205
	global_store_dwordx4 v212, v[202:205], s[100:101]
	v_pk_mul_f32 v[128:129], v[48:49], s[42:43] op_sel_hi:[1,0]
	v_pk_mul_f32 v[130:131], v[50:51], s[42:43] op_sel_hi:[1,0]
	v_pk_mul_f32 v[56:57], v[60:61], v[56:57]
	v_pk_mul_f32 v[58:59], v[62:63], v[58:59]
	v_exp_f32_e32 v128, v128
	v_exp_f32_e32 v129, v129
	v_exp_f32_e32 v130, v130
	v_exp_f32_e32 v131, v131
	v_pk_add_f32 v[128:129], v[128:129], s[42:43] op_sel:[0,1] op_sel_hi:[1,1]
; __device__ __forceinline__ float siluf_(float x) { return x * sigmoidf_(x); }
; __device__ __forceinline__ u32x2 pk4(f32x4 v) { u32x2 r; r.x = pk_bf16(v[0], v[1]); r.y = pk_bf16(v[2], v[3]); return r; }
; template <int CTRL> __device__ __forceinline__ float dppf(float old, float v) { return __int_as_float(__builtin_amdgcn_update_dpp(__float_as_int(old), __float_as_int(v), CTRL, 0xf, 0xf, false)); }
;     __device__ __forceinline__ void operator()(const f32x4 (&acc)[2][2][4][2], const Unit& u, int wr, int wc, int fr, int fq) const {
;     ...
;                             ga[j] = siluf_(Zv[j]) * Bv[j];
;                             const float r1 = (m > 0) ? dppf<0x121>(0.f, pprev[j]) : 0.f, r2 = (m > 0) ? dppf<0x122>(0.f, pprev[j]) : 0.f;
;                             p1[j] = dppf<0x111>(r1, p[j]); p2[j] = dppf<0x112>(r2, p[j]);
;                         }
;                         const f32x4 cv = w2 * p + w1 * p1 + w0 * p2;
;                         hv[m] = pk4(ga * cv);
;                         if (m == 3 && fr >= 14) *(u32x2*)(PAT + (size_t)(blk * 2 + (fr - 14)) * 1024 + ch) = pk4(p);
;                         if (m == 0 && fr < 2) *(u32x2*)(GAH + (size_t)(blk * 2 + fr) * 1024 + ch) = pk4(ga);
	v_pk_add_f32 v[130:131], v[130:131], s[42:43] op_sel:[0,1] op_sel_hi:[1,1]
	v_mov_b32_dpp v132, v56 row_shr:1 row_mask:0xf bank_mask:0xf bound_ctrl:1
	v_mov_b32_dpp v136, v56 row_shr:2 row_mask:0xf bank_mask:0xf bound_ctrl:1
	v_mov_b32_dpp v133, v57 row_shr:1 row_mask:0xf bank_mask:0xf bound_ctrl:1
	v_mov_b32_dpp v137, v57 row_shr:2 row_mask:0xf bank_mask:0xf bound_ctrl:1
	v_mov_b32_dpp v134, v58 row_shr:1 row_mask:0xf bank_mask:0xf bound_ctrl:1
	v_mov_b32_dpp v138, v58 row_shr:2 row_mask:0xf bank_mask:0xf bound_ctrl:1
	v_mov_b32_dpp v135, v59 row_shr:1 row_mask:0xf bank_mask:0xf bound_ctrl:1
	v_mov_b32_dpp v139, v59 row_shr:2 row_mask:0xf bank_mask:0xf bound_ctrl:1
	v_rcp_f32_e32 v128, v128
	v_rcp_f32_e32 v129, v129
	v_rcp_f32_e32 v130, v130
	v_rcp_f32_e32 v131, v131
	v_pk_mul_f32 v[132:133], v[180:181], v[132:133]
	v_pk_mul_f32 v[134:135], v[182:183], v[134:135]
	v_pk_mul_f32 v[128:129], v[48:49], v[128:129]
	v_pk_mul_f32 v[130:131], v[50:51], v[130:131]
	v_pk_fma_f32 v[132:133], v[184:185], v[56:57], v[132:133]
	v_pk_fma_f32 v[134:135], v[186:187], v[58:59], v[134:135]
	v_pk_mul_f32 v[52:53], v[52:53], v[128:129]
	v_pk_mul_f32 v[54:55], v[54:55], v[130:131]
	v_pk_fma_f32 v[132:133], v[176:177], v[136:137], v[132:133]
	v_pk_fma_f32 v[134:135], v[178:179], v[138:139], v[134:135]
	v_cvt_pk_bf16_f32 v208, v52, v53
	v_cvt_pk_bf16_f32 v209, v54, v55
	v_pk_mul_f32 v[132:133], v[52:53], v[132:133]
	v_pk_mul_f32 v[134:135], v[54:55], v[134:135]
	v_cmp_gt_u32_e32 vcc, 2, v241
	s_add_u32 s100, s60, 0x2000
	s_addc_u32 s101, s61, 0
	s_nop 2
	s_and_saveexec_b64 s[4:5], vcc
	global_store_dwordx2 v211, v[208:209], s[100:101]
	s_mov_b64 exec, s[4:5]
	v_cvt_pk_bf16_f32 v198, v132, v133
	v_cvt_pk_bf16_f32 v199, v134, v135
	v_pk_mul_f32 v[128:129], v[16:17], s[42:43] op_sel_hi:[1,0]
	v_pk_mul_f32 v[130:131], v[18:19], s[42:43] op_sel_hi:[1,0]
	v_pk_mul_f32 v[40:41], v[44:45], v[40:41]
	v_pk_mul_f32 v[42:43], v[46:47], v[42:43]
	v_exp_f32_e32 v128, v128
	v_exp_f32_e32 v129, v129
	v_exp_f32_e32 v130, v130
	v_exp_f32_e32 v131, v131
	v_mov_b32_dpp v132, v56 row_ror:1 row_mask:0xf bank_mask:0xf
	v_mov_b32_dpp v136, v56 row_ror:2 row_mask:0xf bank_mask:0xf
	v_mov_b32_dpp v133, v57 row_ror:1 row_mask:0xf bank_mask:0xf
	v_mov_b32_dpp v137, v57 row_ror:2 row_mask:0xf bank_mask:0xf
	v_mov_b32_dpp v134, v58 row_ror:1 row_mask:0xf bank_mask:0xf
	v_mov_b32_dpp v138, v58 row_ror:2 row_mask:0xf bank_mask:0xf
	v_mov_b32_dpp v135, v59 row_ror:1 row_mask:0xf bank_mask:0xf
	v_mov_b32_dpp v139, v59 row_ror:2 row_mask:0xf bank_mask:0xf
	v_pk_add_f32 v[128:129], v[128:129], s[42:43] op_sel:[0,1] op_sel_hi:[1,1]
	v_pk_add_f32 v[130:131], v[130:131], s[42:43] op_sel:[0,1] op_sel_hi:[1,1]
	v_mov_b32_dpp v132, v40 row_shr:1 row_mask:0xf bank_mask:0xf
	v_mov_b32_dpp v136, v40 row_shr:2 row_mask:0xf bank_mask:0xf
	v_mov_b32_dpp v133, v41 row_shr:1 row_mask:0xf bank_mask:0xf
	v_mov_b32_dpp v137, v41 row_shr:2 row_mask:0xf bank_mask:0xf
	v_mov_b32_dpp v134, v42 row_shr:1 row_mask:0xf bank_mask:0xf
	v_mov_b32_dpp v138, v42 row_shr:2 row_mask:0xf bank_mask:0xf
	v_mov_b32_dpp v135, v43 row_shr:1 row_mask:0xf bank_mask:0xf
	v_mov_b32_dpp v139, v43 row_shr:2 row_mask:0xf bank_mask:0xf
	v_rcp_f32_e32 v128, v128
	v_rcp_f32_e32 v129, v129
	v_rcp_f32_e32 v130, v130
	v_rcp_f32_e32 v131, v131
	v_pk_mul_f32 v[132:133], v[180:181], v[132:133]
	v_pk_mul_f32 v[134:135], v[182:183], v[134:135]
	v_pk_mul_f32 v[128:129], v[16:17], v[128:129]
	v_pk_mul_f32 v[130:131], v[18:19], v[130:131]
	v_pk_fma_f32 v[132:133], v[184:185], v[40:41], v[132:133]
	v_pk_fma_f32 v[134:135], v[186:187], v[42:43], v[134:135]
	v_pk_mul_f32 v[20:21], v[20:21], v[128:129]
	v_pk_mul_f32 v[22:23], v[22:23], v[130:131]
	v_pk_fma_f32 v[132:133], v[176:177], v[136:137], v[132:133]
	v_pk_fma_f32 v[134:135], v[178:179], v[138:139], v[134:135]
	v_pk_mul_f32 v[132:133], v[20:21], v[132:133]
	v_pk_mul_f32 v[134:135], v[22:23], v[134:135]
	v_cvt_pk_bf16_f32 v200, v132, v133
	v_cvt_pk_bf16_f32 v201, v134, v135
	v_pk_mul_f32 v[128:129], v[8:9], s[42:43] op_sel_hi:[1,0]
	v_pk_mul_f32 v[130:131], v[10:11], s[42:43] op_sel_hi:[1,0]
	v_pk_mul_f32 v[32:33], v[36:37], v[32:33]
	v_pk_mul_f32 v[34:35], v[38:39], v[34:35]
	v_exp_f32_e32 v128, v128
	v_exp_f32_e32 v129, v129
	v_exp_f32_e32 v130, v130
	v_exp_f32_e32 v131, v131
	v_mov_b32_dpp v132, v40 row_ror:1 row_mask:0xf bank_mask:0xf
	v_mov_b32_dpp v136, v40 row_ror:2 row_mask:0xf bank_mask:0xf
	v_mov_b32_dpp v133, v41 row_ror:1 row_mask:0xf bank_mask:0xf
	v_mov_b32_dpp v137, v41 row_ror:2 row_mask:0xf bank_mask:0xf
; __device__ __forceinline__ float siluf_(float x) { return x * sigmoidf_(x); }
; __device__ __forceinline__ u32x2 pk4(f32x4 v) { u32x2 r; r.x = pk_bf16(v[0], v[1]); r.y = pk_bf16(v[2], v[3]); return r; }
; template <int CTRL> __device__ __forceinline__ float dppf(float old, float v) { return __int_as_float(__builtin_amdgcn_update_dpp(__float_as_int(old), __float_as_int(v), CTRL, 0xf, 0xf, false)); }
;     __device__ __forceinline__ void operator()(const f32x4 (&acc)[2][2][4][2], const Unit& u, int wr, int wc, int fr, int fq) const {
;     ...
;                     for (int m = 0; m < 4; ++m) {
;                         const f32x4 Bv = acc[ai][0][m][0], Cv = acc[ai][0][m][1], Xv = acc[ai][1][m][0], Zv = acc[ai][1][m][1];
;                         const f32x4 p = Cv * Xv; f32x4 ga, p1, p2;
; #pragma unroll
;                         for (int j = 0; j < 4; ++j) {
;                             ga[j] = siluf_(Zv[j]) * Bv[j];
;                             const float r1 = (m > 0) ? dppf<0x121>(0.f, pprev[j]) : 0.f, r2 = (m > 0) ? dppf<0x122>(0.f, pprev[j]) : 0.f;
;                             p1[j] = dppf<0x111>(r1, p[j]); p2[j] = dppf<0x112>(r2, p[j]);
;                         }
;                         const f32x4 cv = w2 * p + w1 * p1 + w0 * p2;
;                         hv[m] = pk4(ga * cv);
;                         if (m == 3 && fr >= 14) *(u32x2*)(PAT + (size_t)(blk * 2 + (fr - 14)) * 1024 + ch) = pk4(p);
;                         if (m == 0 && fr < 2) *(u32x2*)(GAH + (size_t)(blk * 2 + fr) * 1024 + ch) = pk4(ga);
;                         pprev = p;
;                     }
; #pragma unroll
;                     for (int pr = 0; pr < 2; ++pr) store_pair16(HA + (size_t)(rowb + ai * 128 + pr * 32) * 1024 + chw, hv[2 * pr], hv[2 * pr + 1], fq);
	v_mov_b32_dpp v134, v42 row_ror:1 row_mask:0xf bank_mask:0xf
	v_mov_b32_dpp v138, v42 row_ror:2 row_mask:0xf bank_mask:0xf
	v_mov_b32_dpp v135, v43 row_ror:1 row_mask:0xf bank_mask:0xf
	v_mov_b32_dpp v139, v43 row_ror:2 row_mask:0xf bank_mask:0xf
	v_pk_add_f32 v[128:129], v[128:129], s[42:43] op_sel:[0,1] op_sel_hi:[1,1]
	v_pk_add_f32 v[130:131], v[130:131], s[42:43] op_sel:[0,1] op_sel_hi:[1,1]
	v_mov_b32_dpp v132, v32 row_shr:1 row_mask:0xf bank_mask:0xf
	v_mov_b32_dpp v136, v32 row_shr:2 row_mask:0xf bank_mask:0xf
	v_mov_b32_dpp v133, v33 row_shr:1 row_mask:0xf bank_mask:0xf
	v_mov_b32_dpp v137, v33 row_shr:2 row_mask:0xf bank_mask:0xf
	v_mov_b32_dpp v134, v34 row_shr:1 row_mask:0xf bank_mask:0xf
	v_mov_b32_dpp v138, v34 row_shr:2 row_mask:0xf bank_mask:0xf
	v_mov_b32_dpp v135, v35 row_shr:1 row_mask:0xf bank_mask:0xf
	v_mov_b32_dpp v139, v35 row_shr:2 row_mask:0xf bank_mask:0xf
	v_rcp_f32_e32 v128, v128
	v_rcp_f32_e32 v129, v129
	v_rcp_f32_e32 v130, v130
	v_rcp_f32_e32 v131, v131
	v_pk_mul_f32 v[132:133], v[180:181], v[132:133]
	v_pk_mul_f32 v[134:135], v[182:183], v[134:135]
	v_pk_mul_f32 v[128:129], v[8:9], v[128:129]
	v_pk_mul_f32 v[130:131], v[10:11], v[130:131]
	v_pk_fma_f32 v[132:133], v[184:185], v[32:33], v[132:133]
	v_pk_fma_f32 v[134:135], v[186:187], v[34:35], v[134:135]
	v_pk_mul_f32 v[12:13], v[12:13], v[128:129]
	v_pk_mul_f32 v[14:15], v[14:15], v[130:131]
	v_pk_fma_f32 v[132:133], v[176:177], v[136:137], v[132:133]
	v_pk_fma_f32 v[134:135], v[178:179], v[138:139], v[134:135]
	v_pk_mul_f32 v[132:133], v[12:13], v[132:133]
	v_pk_mul_f32 v[134:135], v[14:15], v[134:135]
	v_cvt_pk_bf16_f32 v202, v132, v133
	v_cvt_pk_bf16_f32 v203, v134, v135
	v_pk_mul_f32 v[128:129], v[0:1], s[42:43] op_sel_hi:[1,0]
	v_pk_mul_f32 v[130:131], v[2:3], s[42:43] op_sel_hi:[1,0]
	v_pk_mul_f32 v[24:25], v[28:29], v[24:25]
	v_pk_mul_f32 v[26:27], v[30:31], v[26:27]
	v_exp_f32_e32 v128, v128
	v_exp_f32_e32 v129, v129
	v_exp_f32_e32 v130, v130
	v_exp_f32_e32 v131, v131
	v_mov_b32_dpp v132, v32 row_ror:1 row_mask:0xf bank_mask:0xf
	v_mov_b32_dpp v136, v32 row_ror:2 row_mask:0xf bank_mask:0xf
	v_mov_b32_dpp v133, v33 row_ror:1 row_mask:0xf bank_mask:0xf
	v_mov_b32_dpp v137, v33 row_ror:2 row_mask:0xf bank_mask:0xf
	v_mov_b32_dpp v134, v34 row_ror:1 row_mask:0xf bank_mask:0xf
	v_mov_b32_dpp v138, v34 row_ror:2 row_mask:0xf bank_mask:0xf
	v_mov_b32_dpp v135, v35 row_ror:1 row_mask:0xf bank_mask:0xf
	v_mov_b32_dpp v139, v35 row_ror:2 row_mask:0xf bank_mask:0xf
	v_pk_add_f32 v[128:129], v[128:129], s[42:43] op_sel:[0,1] op_sel_hi:[1,1]
	v_pk_add_f32 v[130:131], v[130:131], s[42:43] op_sel:[0,1] op_sel_hi:[1,1]
	v_mov_b32_dpp v132, v24 row_shr:1 row_mask:0xf bank_mask:0xf
	v_mov_b32_dpp v136, v24 row_shr:2 row_mask:0xf bank_mask:0xf
	v_mov_b32_dpp v133, v25 row_shr:1 row_mask:0xf bank_mask:0xf
	v_mov_b32_dpp v137, v25 row_shr:2 row_mask:0xf bank_mask:0xf
	v_mov_b32_dpp v134, v26 row_shr:1 row_mask:0xf bank_mask:0xf
	v_mov_b32_dpp v138, v26 row_shr:2 row_mask:0xf bank_mask:0xf
	v_mov_b32_dpp v135, v27 row_shr:1 row_mask:0xf bank_mask:0xf
	v_mov_b32_dpp v139, v27 row_shr:2 row_mask:0xf bank_mask:0xf
	v_rcp_f32_e32 v128, v128
	v_rcp_f32_e32 v129, v129
	v_rcp_f32_e32 v130, v130
	v_rcp_f32_e32 v131, v131
	v_pk_mul_f32 v[132:133], v[180:181], v[132:133]
	v_pk_mul_f32 v[134:135], v[182:183], v[134:135]
	v_pk_mul_f32 v[128:129], v[0:1], v[128:129]
	v_pk_mul_f32 v[130:131], v[2:3], v[130:131]
	v_pk_fma_f32 v[132:133], v[184:185], v[24:25], v[132:133]
	v_pk_fma_f32 v[134:135], v[186:187], v[26:27], v[134:135]
	v_pk_mul_f32 v[4:5], v[4:5], v[128:129]
	v_pk_mul_f32 v[6:7], v[6:7], v[130:131]
	v_pk_fma_f32 v[132:133], v[176:177], v[136:137], v[132:133]
	v_pk_fma_f32 v[134:135], v[178:179], v[138:139], v[134:135]
	v_cvt_pk_bf16_f32 v206, v24, v25
	v_cvt_pk_bf16_f32 v207, v26, v27
	v_pk_mul_f32 v[132:133], v[4:5], v[132:133]
	v_pk_mul_f32 v[134:135], v[6:7], v[134:135]
	v_cmp_lt_u32_e32 vcc, 13, v241
	s_sub_u32 s100, s58, 0x5000
	s_subb_u32 s101, s59, 0
	s_nop 2
	s_and_saveexec_b64 s[4:5], vcc
	global_store_dwordx2 v211, v[206:207], s[100:101]
	s_mov_b64 exec, s[4:5]
	v_cvt_pk_bf16_f32 v204, v132, v133
	v_cvt_pk_bf16_f32 v205, v134, v135
	s_add_u32 s100, s98, 0x40000
	s_addc_u32 s101, s99, 0
	v_permlane32_swap_b32_e32 v198, v200
	v_permlane32_swap_b32_e32 v199, v201
	global_store_dwordx4 v212, v[198:201], s[100:101]
	s_add_u32 s100, s98, 0x50000
	s_addc_u32 s101, s99, 0
	v_permlane32_swap_b32_e32 v202, v204
	v_permlane32_swap_b32_e32 v203, v205
	global_store_dwordx4 v212, v[202:205], s[100:101]
	s_branch .LBB0_287
